# stack + accumulator-zeroing peel also in FFN-down and O-proj GEMM instances
# speedup vs baseline: 1.0062x; 1.0062x over previous
.LBB0_311:
	v_readlane_b32 s6, v254, 54
	s_add_u32 s83, s18, 0x12a00000
	v_bfe_u32 v19, v14, 4, 2
	v_readlane_b32 s7, v254, 55
	s_addc_u32 s95, s19, 0
	v_and_b32_e32 v21, 15, v14
	s_lshl_b32 s17, s52, 6
	v_lshlrev_b32_e32 v22, 4, v19
	v_lshlrev_b32_e32 v14, 2, v14
	s_mov_b32 s7, s67
	s_and_b32 s53, s12, 3
	v_or_b32_e32 v20, s17, v21
	v_lshl_or_b32 v21, v21, 6, v22
	s_lshl_b32 s2, s52, 13
	v_and_b32_e32 v14, 32, v14
	s_add_i32 m0, s16, 0x18000
	v_lshl_add_u64 v[8:9], v[8:9], 0, s[74:75]
	v_writelane_b32 v254, s6, 54
	v_bitop3_b32 v22, v21, s2, v14 bitop3:0xde
	s_lshl_b32 s43, s53, 5
	s_lshl_b32 s2, s53, 12
	s_waitcnt vmcnt(2)
	s_barrier
	global_load_lds_dwordx4 v[8:9], off
	v_lshl_add_u64 v[6:7], v[6:7], 0, s[74:75]
	s_add_i32 m0, s16, 0x1a000
	s_add_i32 s70, s16, 0x8000
	s_add_i32 s71, s16, 0xa000
	v_writelane_b32 v254, s7, 55
	global_load_lds_dwordx4 v[6:7], off
	v_lshl_add_u64 v[2:3], v[2:3], 0, s[74:75]
	s_mov_b32 m0, s70
	s_add_u32 s6, s34, 0xb0080
	global_load_lds_dwordx4 v[2:3], off
	v_lshl_add_u64 v[2:3], v[4:5], 0, s[74:75]
	s_mov_b32 m0, s71
	s_addc_u32 s7, s35, 0
	global_load_lds_dwordx4 v[2:3], off
	s_add_i32 m0, s16, 0x1c000
	v_lshl_add_u64 v[2:3], s[6:7], 0, v[0:1]
	global_load_lds_dwordx4 v[2:3], off
	v_lshl_add_u64 v[2:3], s[6:7], 0, v[130:131]
	s_add_i32 m0, s16, 0x1e000
	v_bitop3_b32 v152, v21, s2, v14 bitop3:0xde
	global_load_lds_dwordx4 v[2:3], off
	v_or_b32_e32 v2, 16, v20
	v_ashrrev_i32_e32 v3, 31, v2
	v_ashrrev_i32_e32 v21, 31, v20
	v_lshlrev_b64 v[134:135], 12, v[2:3]
	v_or_b32_e32 v2, 32, v20
	v_lshlrev_b64 v[132:133], 12, v[20:21]
	v_ashrrev_i32_e32 v3, 31, v2
	s_mov_b64 s[6:7], 0x80000
	v_lshlrev_b64 v[136:137], 12, v[2:3]
	v_or_b32_e32 v2, 48, v20
	v_lshl_add_u64 v[140:141], v[132:133], 0, s[6:7]
	s_mov_b64 s[6:7], 0x90000
	v_ashrrev_i32_e32 v3, 31, v2
	v_lshl_add_u64 v[142:143], v[132:133], 0, s[6:7]
	s_mov_b64 s[6:7], 0xa0000
	s_movk_i32 s2, 0xb00
	v_writelane_b32 v253, s12, 16
	v_lshlrev_b64 v[138:139], 12, v[2:3]
	v_lshl_add_u64 v[144:145], v[132:133], 0, s[6:7]
	s_mov_b64 s[6:7], 0xb0000
	v_lshrrev_b32_e32 v3, 1, v16
	v_mul_lo_u32 v2, v15, s2
	s_mov_b32 s12, 0xb000
	v_lshl_add_u64 v[146:147], v[132:133], 0, s[6:7]
	v_mad_u64_u32 v[2:3], s[6:7], v3, s12, v[2:3]
	v_or_b32_e32 v2, v2, v17
	v_add_lshl_u32 v2, v2, v18, 1
	v_mov_b32_e32 v3, v1
	s_mov_b64 s[38:39], 0xb0080
	v_lshl_add_u64 v[148:149], v[2:3], 0, s[38:39]
	v_lshrrev_b32_e32 v3, 1, v10
	v_mul_lo_u32 v2, v11, s2
	v_mad_u64_u32 v[2:3], s[6:7], v3, s12, v[2:3]
	v_or_b32_e32 v2, v2, v12
	s_waitcnt vmcnt(6)
	v_add_lshl_u32 v2, v2, v13, 1
	v_mov_b32_e32 v3, v1
	s_cmpk_lt_u32 s13, 0x100
	v_lshl_add_u64 v[150:151], v[2:3], 0, s[38:39]
	v_cndmask_b32_e64 v153, 0, 1, s[24:25]
	s_cselect_b64 s[30:31], -1, 0
	v_lshl_or_b32 v154, v19, 2, s43
	s_mov_b32 s96, 0
	v_add_u32_e32 v155, 0, v22
	s_barrier

.LBB0_323:
	s_bfe_u32 s59, s97, 0x80014
	s_cmp_lg_u32 s59, 0
	s_cselect_b32 s59, s59, 44
	s_add_i32 s76, s59, -2
	s_add_u32 s91, s34, 0x100
	s_mov_b32 s86, 0
	s_addc_u32 s92, s35, 0
	s_mov_b64 s[80:81], s[36:37]
	s_add_i32 s93, s86, 2
	s_add_u32 s84, s80, 0x100
	s_addc_u32 s85, s81, 0
	s_add_i32 s33, 0, 0x10000
	s_cmp_eq_u32 s76, s86
	s_cselect_b32 vcc_hi, s63, s85
	s_cselect_b32 vcc_lo, s62, s84
	s_cselect_b32 s87, s65, s92
	s_cselect_b32 s86, s64, s91
	s_add_i32 s51, 0, 0x14000
	v_add_u32_e32 v168, s33, v152
	v_add_u32_e32 v176, s51, v152
	ds_read_b128 v[156:159], v168
	ds_read_b128 v[160:163], v168 offset:1024
	ds_read_b128 v[164:167], v168 offset:2048
	ds_read_b128 v[168:171], v168 offset:3072
	ds_read_b128 v[172:175], v176
	ds_read_b128 v[180:183], v176 offset:1024
	ds_read_b128 v[184:187], v176 offset:2048
	ds_read_b128 v[188:191], v176 offset:3072
	v_lshl_add_u64 v[176:177], s[80:81], 0, v[148:149]
	s_add_i32 m0, s16, 0xc000
	ds_read_b128 v[192:195], v155
	ds_read_b128 v[196:199], v155 offset:1024
	ds_read_b128 v[200:203], v155 offset:2048
	ds_read_b128 v[204:207], v155 offset:3072
	ds_read_b128 v[208:211], v155 offset:4096
	ds_read_b128 v[212:215], v155 offset:5120
	ds_read_b128 v[216:219], v155 offset:6144
	ds_read_b128 v[220:223], v155 offset:7168
	global_load_lds_dwordx4 v[176:177], off
	v_lshl_add_u64 v[176:177], s[80:81], 0, v[150:151]
	s_add_i32 m0, s16, 0xe000
	s_nop 0
	global_load_lds_dwordx4 v[176:177], off
	s_waitcnt vmcnt(8)
	s_waitcnt lgkmcnt(0)
	s_barrier
	s_setprio 1
	s_waitcnt lgkmcnt(0)
	v_mfma_f32_16x16x32_bf16 v[126:129], v[156:159], v[192:195], 0
	v_mfma_f32_16x16x32_bf16 v[106:109], v[164:167], v[192:195], 0
	v_mfma_f32_16x16x32_bf16 v[122:125], v[156:159], v[200:203], 0
	v_mfma_f32_16x16x32_bf16 v[98:101], v[164:167], v[200:203], 0
	v_mfma_f32_16x16x32_bf16 v[118:121], v[156:159], v[208:211], 0
	v_mfma_f32_16x16x32_bf16 v[90:93], v[164:167], v[208:211], 0
	v_mfma_f32_16x16x32_bf16 v[114:117], v[156:159], v[216:219], 0
	v_mfma_f32_16x16x32_bf16 v[78:81], v[164:167], v[216:219], 0
	v_mfma_f32_16x16x32_bf16 v[126:129], v[160:163], v[196:199], v[126:129]
	v_mfma_f32_16x16x32_bf16 v[106:109], v[168:171], v[196:199], v[106:109]
	v_mfma_f32_16x16x32_bf16 v[122:125], v[160:163], v[204:207], v[122:125]
	v_mfma_f32_16x16x32_bf16 v[98:101], v[168:171], v[204:207], v[98:101]
	v_mfma_f32_16x16x32_bf16 v[118:121], v[160:163], v[212:215], v[118:121]
	v_mfma_f32_16x16x32_bf16 v[90:93], v[168:171], v[212:215], v[90:93]
	v_mfma_f32_16x16x32_bf16 v[114:117], v[160:163], v[220:223], v[114:117]
	v_mfma_f32_16x16x32_bf16 v[78:81], v[168:171], v[220:223], v[78:81]
	s_setprio 0
	s_setprio 1
	v_mfma_f32_16x16x32_bf16 v[66:69], v[172:175], v[192:195], 0
	v_mfma_f32_16x16x32_bf16 v[86:89], v[184:187], v[192:195], 0
	v_mfma_f32_16x16x32_bf16 v[54:57], v[172:175], v[200:203], 0
	v_mfma_f32_16x16x32_bf16 v[82:85], v[184:187], v[200:203], 0
	v_mfma_f32_16x16x32_bf16 v[46:49], v[172:175], v[208:211], 0
	v_mfma_f32_16x16x32_bf16 v[26:29], v[184:187], v[208:211], 0
	v_mfma_f32_16x16x32_bf16 v[42:45], v[172:175], v[216:219], 0
	v_mfma_f32_16x16x32_bf16 v[18:21], v[184:187], v[216:219], 0
	v_mfma_f32_16x16x32_bf16 v[66:69], v[180:183], v[196:199], v[66:69]
	v_mfma_f32_16x16x32_bf16 v[86:89], v[188:191], v[196:199], v[86:89]
	v_mfma_f32_16x16x32_bf16 v[54:57], v[180:183], v[204:207], v[54:57]
	v_mfma_f32_16x16x32_bf16 v[82:85], v[188:191], v[204:207], v[82:85]
	v_mfma_f32_16x16x32_bf16 v[46:49], v[180:183], v[212:215], v[46:49]
	v_mfma_f32_16x16x32_bf16 v[26:29], v[188:191], v[212:215], v[26:29]
	v_mfma_f32_16x16x32_bf16 v[42:45], v[180:183], v[220:223], v[42:45]
	v_mfma_f32_16x16x32_bf16 v[18:21], v[188:191], v[220:223], v[18:21]
	s_setprio 0
	s_barrier
	s_add_i32 s33, s33, s14
	v_lshl_add_u64 v[176:177], s[86:87], 0, v[0:1]
	s_mov_b32 m0, s33
	ds_read_b128 v[192:195], v155 offset:16384
	ds_read_b128 v[196:199], v155 offset:17408
	ds_read_b128 v[200:203], v155 offset:18432
	ds_read_b128 v[204:207], v155 offset:19456
	ds_read_b128 v[208:211], v155 offset:20480
	ds_read_b128 v[212:215], v155 offset:21504
	ds_read_b128 v[216:219], v155 offset:22528
	ds_read_b128 v[220:223], v155 offset:23552
	global_load_lds_dwordx4 v[176:177], off
	s_add_i32 m0, s33, 0x2000
	s_add_u32 s80, s86, 0xb0000
	v_lshl_add_u64 v[224:225], s[86:87], 0, v[130:131]
	s_addc_u32 s81, s87, 0
	s_add_i32 s33, s51, s14
	global_load_lds_dwordx4 v[224:225], off
	v_lshl_add_u64 v[226:227], s[80:81], 0, v[0:1]
	s_mov_b32 m0, s33
	v_lshl_add_u64 v[228:229], vcc, 0, v[130:131]
	global_load_lds_dwordx4 v[226:227], off
	v_lshl_add_u64 v[226:227], s[80:81], 0, v[130:131]
	s_add_i32 m0, s33, 0x2000
	s_nop 0
	global_load_lds_dwordx4 v[226:227], off
	v_lshl_add_u64 v[226:227], vcc, 0, v[0:1]
	s_mov_b32 m0, s16
	s_nop 0
	global_load_lds_dwordx4 v[226:227], off
	s_mov_b32 m0, s23
	s_nop 0
	global_load_lds_dwordx4 v[228:229], off
	s_waitcnt vmcnt(8)
	s_waitcnt lgkmcnt(0)
	s_barrier
	s_setprio 1
	s_waitcnt lgkmcnt(0)
	v_mfma_f32_16x16x32_bf16 v[110:113], v[156:159], v[192:195], 0
	v_mfma_f32_16x16x32_bf16 v[70:73], v[164:167], v[192:195], 0
	v_mfma_f32_16x16x32_bf16 v[102:105], v[156:159], v[200:203], 0
	v_mfma_f32_16x16x32_bf16 v[62:65], v[164:167], v[200:203], 0
	v_mfma_f32_16x16x32_bf16 v[94:97], v[156:159], v[208:211], 0
	v_mfma_f32_16x16x32_bf16 v[58:61], v[164:167], v[208:211], 0
	v_mfma_f32_16x16x32_bf16 v[74:77], v[156:159], v[216:219], 0
	v_mfma_f32_16x16x32_bf16 v[50:53], v[164:167], v[216:219], 0
	v_mfma_f32_16x16x32_bf16 v[110:113], v[160:163], v[196:199], v[110:113]
	v_mfma_f32_16x16x32_bf16 v[70:73], v[168:171], v[196:199], v[70:73]
	v_mfma_f32_16x16x32_bf16 v[102:105], v[160:163], v[204:207], v[102:105]
	v_mfma_f32_16x16x32_bf16 v[62:65], v[168:171], v[204:207], v[62:65]
	v_mfma_f32_16x16x32_bf16 v[94:97], v[160:163], v[212:215], v[94:97]
	v_mfma_f32_16x16x32_bf16 v[58:61], v[168:171], v[212:215], v[58:61]
	v_mfma_f32_16x16x32_bf16 v[74:77], v[160:163], v[220:223], v[74:77]
	v_mfma_f32_16x16x32_bf16 v[50:53], v[168:171], v[220:223], v[50:53]
	s_setprio 0
	s_setprio 1
	v_mfma_f32_16x16x32_bf16 v[38:41], v[172:175], v[192:195], 0
	v_mfma_f32_16x16x32_bf16 v[14:17], v[184:187], v[192:195], 0
	v_mfma_f32_16x16x32_bf16 v[34:37], v[172:175], v[200:203], 0
	v_mfma_f32_16x16x32_bf16 v[10:13], v[184:187], v[200:203], 0
	v_mfma_f32_16x16x32_bf16 v[30:33], v[172:175], v[208:211], 0
	v_mfma_f32_16x16x32_bf16 v[6:9], v[184:187], v[208:211], 0
	v_mfma_f32_16x16x32_bf16 v[22:25], v[172:175], v[216:219], 0
	v_mfma_f32_16x16x32_bf16 v[2:5], v[184:187], v[216:219], 0
	v_mfma_f32_16x16x32_bf16 v[38:41], v[180:183], v[196:199], v[38:41]
	v_mfma_f32_16x16x32_bf16 v[14:17], v[188:191], v[196:199], v[14:17]
	v_mfma_f32_16x16x32_bf16 v[34:37], v[180:183], v[204:207], v[34:37]
	v_mfma_f32_16x16x32_bf16 v[10:13], v[188:191], v[204:207], v[10:13]
	v_mfma_f32_16x16x32_bf16 v[30:33], v[180:183], v[212:215], v[30:33]
	v_mfma_f32_16x16x32_bf16 v[6:9], v[188:191], v[212:215], v[6:9]
	v_mfma_f32_16x16x32_bf16 v[22:25], v[180:183], v[220:223], v[22:25]
	v_mfma_f32_16x16x32_bf16 v[2:5], v[188:191], v[220:223], v[2:5]
	s_setprio 0
	s_barrier
	s_branch .Lmy_mid_down

.Lmy_mid_down:
	s_add_i32 s33, 0, 0x18000
	s_add_i32 s51, 0, 0x1c000
	v_add_u32_e32 v168, s33, v152
	v_add_u32_e32 v188, s51, v152
	ds_read_b128 v[156:159], v168
	ds_read_b128 v[160:163], v168 offset:1024
	ds_read_b128 v[164:167], v168 offset:2048
	ds_read_b128 v[168:171], v168 offset:3072
	ds_read_b128 v[172:175], v188
	ds_read_b128 v[180:183], v188 offset:1024
	ds_read_b128 v[184:187], v188 offset:2048
	ds_read_b128 v[188:191], v188 offset:3072
	s_add_u32 s80, vcc_lo, 0xb0000
	s_addc_u32 s81, vcc_hi, 0
	s_mov_b32 m0, s48
	v_lshl_add_u64 v[230:231], s[80:81], 0, v[0:1]
	ds_read_b128 v[192:195], v155 offset:32768
	ds_read_b128 v[196:199], v155 offset:33792
	ds_read_b128 v[200:203], v155 offset:34816
	ds_read_b128 v[204:207], v155 offset:35840
	ds_read_b128 v[208:211], v155 offset:36864
	ds_read_b128 v[212:215], v155 offset:37888
	ds_read_b128 v[216:219], v155 offset:38912
	ds_read_b128 v[220:223], v155 offset:39936
	global_load_lds_dwordx4 v[230:231], off
	v_lshl_add_u64 v[230:231], s[80:81], 0, v[130:131]
	s_mov_b32 m0, s49
	s_nop 0
	global_load_lds_dwordx4 v[230:231], off
	s_waitcnt vmcnt(8)
	s_waitcnt lgkmcnt(0)
	s_barrier
	s_setprio 1
	s_waitcnt lgkmcnt(0)
	v_mfma_f32_16x16x32_bf16 v[126:129], v[156:159], v[192:195], v[126:129]
	v_mfma_f32_16x16x32_bf16 v[106:109], v[164:167], v[192:195], v[106:109]
	v_mfma_f32_16x16x32_bf16 v[122:125], v[156:159], v[200:203], v[122:125]
	v_mfma_f32_16x16x32_bf16 v[98:101], v[164:167], v[200:203], v[98:101]
	v_mfma_f32_16x16x32_bf16 v[118:121], v[156:159], v[208:211], v[118:121]
	v_mfma_f32_16x16x32_bf16 v[90:93], v[164:167], v[208:211], v[90:93]
	v_mfma_f32_16x16x32_bf16 v[114:117], v[156:159], v[216:219], v[114:117]
	v_mfma_f32_16x16x32_bf16 v[78:81], v[164:167], v[216:219], v[78:81]
	v_mfma_f32_16x16x32_bf16 v[126:129], v[160:163], v[196:199], v[126:129]
	v_mfma_f32_16x16x32_bf16 v[106:109], v[168:171], v[196:199], v[106:109]
	v_mfma_f32_16x16x32_bf16 v[122:125], v[160:163], v[204:207], v[122:125]
	v_mfma_f32_16x16x32_bf16 v[98:101], v[168:171], v[204:207], v[98:101]
	v_mfma_f32_16x16x32_bf16 v[118:121], v[160:163], v[212:215], v[118:121]
	v_mfma_f32_16x16x32_bf16 v[90:93], v[168:171], v[212:215], v[90:93]
	v_mfma_f32_16x16x32_bf16 v[114:117], v[160:163], v[220:223], v[114:117]
	v_mfma_f32_16x16x32_bf16 v[78:81], v[168:171], v[220:223], v[78:81]
	s_setprio 0
	s_setprio 1
	v_mfma_f32_16x16x32_bf16 v[66:69], v[172:175], v[192:195], v[66:69]
	v_mfma_f32_16x16x32_bf16 v[86:89], v[184:187], v[192:195], v[86:89]
	v_mfma_f32_16x16x32_bf16 v[54:57], v[172:175], v[200:203], v[54:57]
	v_mfma_f32_16x16x32_bf16 v[82:85], v[184:187], v[200:203], v[82:85]
	v_mfma_f32_16x16x32_bf16 v[46:49], v[172:175], v[208:211], v[46:49]
	v_mfma_f32_16x16x32_bf16 v[26:29], v[184:187], v[208:211], v[26:29]
	v_mfma_f32_16x16x32_bf16 v[42:45], v[172:175], v[216:219], v[42:45]
	v_mfma_f32_16x16x32_bf16 v[18:21], v[184:187], v[216:219], v[18:21]
	v_mfma_f32_16x16x32_bf16 v[66:69], v[180:183], v[196:199], v[66:69]
	v_mfma_f32_16x16x32_bf16 v[86:89], v[188:191], v[196:199], v[86:89]
	v_mfma_f32_16x16x32_bf16 v[54:57], v[180:183], v[204:207], v[54:57]
	v_mfma_f32_16x16x32_bf16 v[82:85], v[188:191], v[204:207], v[82:85]
	v_mfma_f32_16x16x32_bf16 v[46:49], v[180:183], v[212:215], v[46:49]
	v_mfma_f32_16x16x32_bf16 v[26:29], v[188:191], v[212:215], v[26:29]
	v_mfma_f32_16x16x32_bf16 v[42:45], v[180:183], v[220:223], v[42:45]
	v_mfma_f32_16x16x32_bf16 v[18:21], v[188:191], v[220:223], v[18:21]
	s_setprio 0
	s_barrier
	s_add_i32 s33, s33, s14
	v_lshl_add_u64 v[176:177], v[176:177], 0, s[74:75]
	s_mov_b32 m0, s33
	ds_read_b128 v[192:195], v155 offset:49152
	ds_read_b128 v[196:199], v155 offset:50176
	ds_read_b128 v[200:203], v155 offset:51200
	ds_read_b128 v[204:207], v155 offset:52224
	ds_read_b128 v[208:211], v155 offset:53248
	ds_read_b128 v[212:215], v155 offset:54272
	ds_read_b128 v[216:219], v155 offset:55296
	ds_read_b128 v[220:223], v155 offset:56320
	global_load_lds_dwordx4 v[176:177], off
	s_add_i32 m0, s33, 0x2000
	s_add_u32 s80, s86, 0xb0080
	v_lshl_add_u64 v[176:177], v[224:225], 0, s[74:75]
	s_addc_u32 s81, s87, 0
	s_add_i32 s33, s51, s14
	global_load_lds_dwordx4 v[176:177], off
	v_lshl_add_u64 v[176:177], s[80:81], 0, v[0:1]
	s_mov_b32 m0, s33
	s_nop 0
	global_load_lds_dwordx4 v[176:177], off
	v_lshl_add_u64 v[176:177], s[80:81], 0, v[130:131]
	s_add_i32 m0, s33, 0x2000
	s_nop 0
	global_load_lds_dwordx4 v[176:177], off
	v_lshl_add_u64 v[176:177], v[226:227], 0, s[74:75]
	s_mov_b32 m0, s70
	s_nop 0
	global_load_lds_dwordx4 v[176:177], off
	v_lshl_add_u64 v[176:177], v[228:229], 0, s[74:75]
	s_mov_b32 m0, s71
	s_nop 0
	global_load_lds_dwordx4 v[176:177], off
	s_waitcnt vmcnt(8)
	s_waitcnt lgkmcnt(0)
	s_barrier
	s_setprio 1
	s_waitcnt lgkmcnt(0)
	v_mfma_f32_16x16x32_bf16 v[110:113], v[156:159], v[192:195], v[110:113]
	v_mfma_f32_16x16x32_bf16 v[70:73], v[164:167], v[192:195], v[70:73]
	v_mfma_f32_16x16x32_bf16 v[102:105], v[156:159], v[200:203], v[102:105]
	v_mfma_f32_16x16x32_bf16 v[62:65], v[164:167], v[200:203], v[62:65]
	v_mfma_f32_16x16x32_bf16 v[94:97], v[156:159], v[208:211], v[94:97]
	v_mfma_f32_16x16x32_bf16 v[58:61], v[164:167], v[208:211], v[58:61]
	v_mfma_f32_16x16x32_bf16 v[74:77], v[156:159], v[216:219], v[74:77]
	v_mfma_f32_16x16x32_bf16 v[50:53], v[164:167], v[216:219], v[50:53]
	v_mfma_f32_16x16x32_bf16 v[110:113], v[160:163], v[196:199], v[110:113]
	v_mfma_f32_16x16x32_bf16 v[70:73], v[168:171], v[196:199], v[70:73]
	v_mfma_f32_16x16x32_bf16 v[102:105], v[160:163], v[204:207], v[102:105]
	v_mfma_f32_16x16x32_bf16 v[62:65], v[168:171], v[204:207], v[62:65]
	v_mfma_f32_16x16x32_bf16 v[94:97], v[160:163], v[212:215], v[94:97]
	v_mfma_f32_16x16x32_bf16 v[58:61], v[168:171], v[212:215], v[58:61]
	v_mfma_f32_16x16x32_bf16 v[74:77], v[160:163], v[220:223], v[74:77]
	v_mfma_f32_16x16x32_bf16 v[50:53], v[168:171], v[220:223], v[50:53]
	s_setprio 0
	s_setprio 1
	v_mfma_f32_16x16x32_bf16 v[38:41], v[172:175], v[192:195], v[38:41]
	v_mfma_f32_16x16x32_bf16 v[14:17], v[184:187], v[192:195], v[14:17]
	v_mfma_f32_16x16x32_bf16 v[34:37], v[172:175], v[200:203], v[34:37]
	v_mfma_f32_16x16x32_bf16 v[10:13], v[184:187], v[200:203], v[10:13]
	v_mfma_f32_16x16x32_bf16 v[30:33], v[172:175], v[208:211], v[30:33]
	v_mfma_f32_16x16x32_bf16 v[6:9], v[184:187], v[208:211], v[6:9]
	v_mfma_f32_16x16x32_bf16 v[22:25], v[172:175], v[216:219], v[22:25]
	v_mfma_f32_16x16x32_bf16 v[2:5], v[184:187], v[216:219], v[2:5]
	v_mfma_f32_16x16x32_bf16 v[38:41], v[180:183], v[196:199], v[38:41]
	v_mfma_f32_16x16x32_bf16 v[14:17], v[188:191], v[196:199], v[14:17]
	v_mfma_f32_16x16x32_bf16 v[34:37], v[180:183], v[204:207], v[34:37]
	v_mfma_f32_16x16x32_bf16 v[10:13], v[188:191], v[204:207], v[10:13]
	v_mfma_f32_16x16x32_bf16 v[30:33], v[180:183], v[212:215], v[30:33]
	v_mfma_f32_16x16x32_bf16 v[6:9], v[188:191], v[212:215], v[6:9]
	v_mfma_f32_16x16x32_bf16 v[22:25], v[180:183], v[220:223], v[22:25]
	v_mfma_f32_16x16x32_bf16 v[2:5], v[188:191], v[220:223], v[2:5]
	s_setprio 0
	s_barrier
	s_add_u32 s91, s91, 0x100
	s_addc_u32 s92, s92, 0
	s_cmp_ge_u32 s93, s59
	s_mov_b64 s[80:81], s[84:85]
	s_mov_b32 s86, s93
	s_cbranch_scc0 .LBB0_324
	s_and_b64 vcc, exec, s[30:31]
	s_movk_i32 s86, 0xff5e
	s_cbranch_vccz .LBB0_327
	s_barrier

.LBB0_330:
	s_nop 0
	s_mov_b32 s97, s79
	s_mov_b32 s22, s2
	s_mov_b32 s82, s12
	s_andn2_b64 vcc, exec, s[38:39]
	s_cbranch_vccnz .LBB0_332
	s_branch .LBB0_333

.LBB0_1151:
	s_add_u32 s15, s12, 0x12a00000
	v_bfe_u32 v19, v13, 4, 2
	s_addc_u32 s52, s13, 0
	v_and_b32_e32 v21, 15, v13
	s_lshl_b32 s87, s68, 6
	v_lshlrev_b32_e32 v22, 4, v19
	v_lshlrev_b32_e32 v13, 2, v13
	s_and_b32 s6, s22, 3
	v_or_b32_e32 v20, s87, v21
	v_lshl_or_b32 v21, v21, 6, v22
	s_lshl_b32 s2, s68, 13
	v_and_b32_e32 v13, 32, v13
	s_add_i32 m0, s17, 0x18000
	v_lshl_add_u64 v[8:9], v[8:9], 0, s[74:75]
	v_bitop3_b32 v22, v21, s2, v13 bitop3:0xde
	s_lshl_b32 s43, s6, 5
	s_lshl_b32 s2, s6, 12
	s_waitcnt vmcnt(2)
	s_barrier
	global_load_lds_dwordx4 v[8:9], off
	v_lshl_add_u64 v[6:7], v[6:7], 0, s[74:75]
	s_add_i32 m0, s17, 0x1a000
	s_add_i32 s83, s17, 0x8000
	s_add_i32 s70, s17, 0xa000
	s_mov_b32 s92, s6
	global_load_lds_dwordx4 v[6:7], off
	v_lshl_add_u64 v[2:3], v[2:3], 0, s[74:75]
	s_mov_b32 m0, s83
	s_add_u32 s6, s24, 0x40080
	global_load_lds_dwordx4 v[2:3], off
	v_lshl_add_u64 v[2:3], v[4:5], 0, s[74:75]
	s_mov_b32 m0, s70
	s_addc_u32 s7, s25, 0
	global_load_lds_dwordx4 v[2:3], off
	s_add_i32 m0, s17, 0x1c000
	v_lshl_add_u64 v[2:3], s[6:7], 0, v[0:1]
	global_load_lds_dwordx4 v[2:3], off
	v_lshl_add_u64 v[2:3], s[6:7], 0, v[130:131]
	s_add_i32 m0, s17, 0x1e000
	v_bitop3_b32 v152, v21, s2, v13 bitop3:0xde
	global_load_lds_dwordx4 v[2:3], off
	v_or_b32_e32 v2, 16, v20
	v_ashrrev_i32_e32 v3, 31, v2
	v_lshlrev_b64 v[134:135], 12, v[2:3]
	v_or_b32_e32 v2, 32, v20
	v_ashrrev_i32_e32 v3, 31, v2
	v_lshlrev_b64 v[136:137], 12, v[2:3]
	v_or_b32_e32 v2, 48, v20
	v_ashrrev_i32_e32 v21, 31, v20
	v_ashrrev_i32_e32 v3, 31, v2
	v_lshlrev_b64 v[132:133], 12, v[20:21]
	v_lshlrev_b64 v[138:139], 12, v[2:3]
	s_mov_b64 s[6:7], 0x80000
	v_lshlrev_b32_e32 v2, 13, v16
	v_lshl_add_u64 v[140:141], v[132:133], 0, s[6:7]
	s_mov_b64 s[6:7], 0x90000
	v_and_b32_e32 v2, 0x7fffc000, v2
	v_lshl_add_u64 v[142:143], v[132:133], 0, s[6:7]
	s_mov_b64 s[6:7], 0xa0000
	v_lshl_add_u32 v2, v15, 10, v2
	v_lshl_add_u64 v[144:145], v[132:133], 0, s[6:7]
	s_mov_b64 s[6:7], 0xb0000
	v_or_b32_e32 v2, v2, v17
	v_lshl_add_u64 v[146:147], v[132:133], 0, s[6:7]
	v_add_lshl_u32 v2, v2, v18, 1
	v_mov_b32_e32 v3, v1
	s_mov_b64 s[6:7], 0x40080
	v_lshl_add_u64 v[148:149], v[2:3], 0, s[6:7]
	v_lshlrev_b32_e32 v2, 13, v10
	v_and_b32_e32 v2, 0x7fffc000, v2
	v_lshl_add_u32 v2, v11, 10, v2
	v_or_b32_e32 v2, v2, v12
	s_waitcnt vmcnt(6)
	v_add_lshl_u32 v2, v2, v14, 1
	s_cmpk_lt_u32 s97, 0x100
	v_lshl_add_u64 v[150:151], v[2:3], 0, s[6:7]
	v_writelane_b32 v253, s22, 13
	s_cselect_b64 s[22:23], -1, 0
	v_cndmask_b32_e64 v153, 0, 1, s[18:19]
	v_lshl_or_b32 v154, v19, 2, s43
	s_mov_b32 s2, 0
	v_add_u32_e32 v155, 0, v22
	s_waitcnt vmcnt(0)
	s_barrier

.LBB0_1163:
	s_bfe_u32 s29, s86, 0x80014
	s_cmp_lg_u32 s29, 0
	s_cselect_b32 s29, s29, 16
	s_add_i32 s31, s29, -2
	s_add_u32 s59, s24, 0x100
	s_mov_b32 s80, 0
	s_addc_u32 s76, s25, 0
	s_mov_b64 s[62:63], s[26:27]
	s_add_i32 s82, s80, 2
	s_add_u32 s64, s62, 0x100
	s_addc_u32 s65, s63, 0
	s_add_i32 s33, 0, 0x10000
	s_cmp_eq_u32 s31, s80
	s_cselect_b32 s85, s37, s65
	s_cselect_b32 s84, s36, s64
	s_cselect_b32 s81, s39, s76
	s_cselect_b32 s80, s38, s59
	s_add_i32 s51, 0, 0x14000
	v_add_u32_e32 v168, s33, v152
	v_add_u32_e32 v176, s51, v152
	ds_read_b128 v[156:159], v168
	ds_read_b128 v[160:163], v168 offset:1024
	ds_read_b128 v[164:167], v168 offset:2048
	ds_read_b128 v[168:171], v168 offset:3072
	ds_read_b128 v[172:175], v176
	ds_read_b128 v[180:183], v176 offset:1024
	ds_read_b128 v[184:187], v176 offset:2048
	ds_read_b128 v[188:191], v176 offset:3072
	v_lshl_add_u64 v[176:177], s[62:63], 0, v[148:149]
	s_add_i32 m0, s17, 0xc000
	ds_read_b128 v[192:195], v155
	ds_read_b128 v[196:199], v155 offset:1024
	ds_read_b128 v[200:203], v155 offset:2048
	ds_read_b128 v[204:207], v155 offset:3072
	ds_read_b128 v[208:211], v155 offset:4096
	ds_read_b128 v[212:215], v155 offset:5120
	ds_read_b128 v[216:219], v155 offset:6144
	ds_read_b128 v[220:223], v155 offset:7168
	global_load_lds_dwordx4 v[176:177], off
	v_lshl_add_u64 v[176:177], s[62:63], 0, v[150:151]
	s_add_i32 m0, s17, 0xe000
	s_nop 0
	global_load_lds_dwordx4 v[176:177], off
	s_waitcnt vmcnt(8)
	s_waitcnt lgkmcnt(0)
	s_barrier
	s_setprio 1
	s_waitcnt lgkmcnt(0)
	v_mfma_f32_16x16x32_bf16 v[122:125], v[156:159], v[192:195], 0
	v_mfma_f32_16x16x32_bf16 v[102:105], v[164:167], v[192:195], 0
	v_mfma_f32_16x16x32_bf16 v[118:121], v[156:159], v[200:203], 0
	v_mfma_f32_16x16x32_bf16 v[94:97], v[164:167], v[200:203], 0
	v_mfma_f32_16x16x32_bf16 v[114:117], v[156:159], v[208:211], 0
	v_mfma_f32_16x16x32_bf16 v[90:93], v[164:167], v[208:211], 0
	v_mfma_f32_16x16x32_bf16 v[110:113], v[156:159], v[216:219], 0
	v_mfma_f32_16x16x32_bf16 v[82:85], v[164:167], v[216:219], 0
	v_mfma_f32_16x16x32_bf16 v[122:125], v[160:163], v[196:199], v[122:125]
	v_mfma_f32_16x16x32_bf16 v[102:105], v[168:171], v[196:199], v[102:105]
	v_mfma_f32_16x16x32_bf16 v[118:121], v[160:163], v[204:207], v[118:121]
	v_mfma_f32_16x16x32_bf16 v[94:97], v[168:171], v[204:207], v[94:97]
	v_mfma_f32_16x16x32_bf16 v[114:117], v[160:163], v[212:215], v[114:117]
	v_mfma_f32_16x16x32_bf16 v[90:93], v[168:171], v[212:215], v[90:93]
	v_mfma_f32_16x16x32_bf16 v[110:113], v[160:163], v[220:223], v[110:113]
	v_mfma_f32_16x16x32_bf16 v[82:85], v[168:171], v[220:223], v[82:85]
	s_setprio 0
	s_setprio 1
	v_mfma_f32_16x16x32_bf16 v[70:73], v[172:175], v[192:195], 0
	v_mfma_f32_16x16x32_bf16 v[126:129], v[184:187], v[192:195], 0
	v_mfma_f32_16x16x32_bf16 v[66:69], v[172:175], v[200:203], 0
	v_mfma_f32_16x16x32_bf16 v[42:45], v[184:187], v[200:203], 0
	v_mfma_f32_16x16x32_bf16 v[50:53], v[172:175], v[208:211], 0
	v_mfma_f32_16x16x32_bf16 v[30:33], v[184:187], v[208:211], 0
	v_mfma_f32_16x16x32_bf16 v[46:49], v[172:175], v[216:219], 0
	v_mfma_f32_16x16x32_bf16 v[26:29], v[184:187], v[216:219], 0
	v_mfma_f32_16x16x32_bf16 v[70:73], v[180:183], v[196:199], v[70:73]
	v_mfma_f32_16x16x32_bf16 v[126:129], v[188:191], v[196:199], v[126:129]
	v_mfma_f32_16x16x32_bf16 v[66:69], v[180:183], v[204:207], v[66:69]
	v_mfma_f32_16x16x32_bf16 v[42:45], v[188:191], v[204:207], v[42:45]
	v_mfma_f32_16x16x32_bf16 v[50:53], v[180:183], v[212:215], v[50:53]
	v_mfma_f32_16x16x32_bf16 v[30:33], v[188:191], v[212:215], v[30:33]
	v_mfma_f32_16x16x32_bf16 v[46:49], v[180:183], v[220:223], v[46:49]
	v_mfma_f32_16x16x32_bf16 v[26:29], v[188:191], v[220:223], v[26:29]
	s_setprio 0
	s_barrier
	s_add_i32 s33, s33, s79
	v_lshl_add_u64 v[176:177], s[80:81], 0, v[0:1]
	s_mov_b32 m0, s33
	ds_read_b128 v[192:195], v155 offset:16384
	ds_read_b128 v[196:199], v155 offset:17408
	ds_read_b128 v[200:203], v155 offset:18432
	ds_read_b128 v[204:207], v155 offset:19456
	ds_read_b128 v[208:211], v155 offset:20480
	ds_read_b128 v[212:215], v155 offset:21504
	ds_read_b128 v[216:219], v155 offset:22528
	ds_read_b128 v[220:223], v155 offset:23552
	global_load_lds_dwordx4 v[176:177], off
	s_add_i32 m0, s33, 0x2000
	s_add_u32 s62, s80, 0x40000
	v_lshl_add_u64 v[224:225], s[80:81], 0, v[130:131]
	s_addc_u32 s63, s81, 0
	s_add_i32 s33, s51, s79
	global_load_lds_dwordx4 v[224:225], off
	v_lshl_add_u64 v[226:227], s[62:63], 0, v[0:1]
	s_mov_b32 m0, s33
	v_lshl_add_u64 v[228:229], s[84:85], 0, v[130:131]
	global_load_lds_dwordx4 v[226:227], off
	v_lshl_add_u64 v[226:227], s[62:63], 0, v[130:131]
	s_add_i32 m0, s33, 0x2000
	s_nop 0
	global_load_lds_dwordx4 v[226:227], off
	v_lshl_add_u64 v[226:227], s[84:85], 0, v[0:1]
	s_mov_b32 m0, s17
	s_nop 0
	global_load_lds_dwordx4 v[226:227], off
	s_mov_b32 m0, s53
	s_nop 0
	global_load_lds_dwordx4 v[228:229], off
	s_waitcnt vmcnt(8)
	s_waitcnt lgkmcnt(0)
	s_barrier
	s_setprio 1
	s_waitcnt lgkmcnt(0)
	v_mfma_f32_16x16x32_bf16 v[106:109], v[156:159], v[192:195], 0
	v_mfma_f32_16x16x32_bf16 v[74:77], v[164:167], v[192:195], 0
	v_mfma_f32_16x16x32_bf16 v[98:101], v[156:159], v[200:203], 0
	v_mfma_f32_16x16x32_bf16 v[62:65], v[164:167], v[200:203], 0
	v_mfma_f32_16x16x32_bf16 v[86:89], v[156:159], v[208:211], 0
	v_mfma_f32_16x16x32_bf16 v[58:61], v[164:167], v[208:211], 0
	v_mfma_f32_16x16x32_bf16 v[78:81], v[156:159], v[216:219], 0
	v_mfma_f32_16x16x32_bf16 v[54:57], v[164:167], v[216:219], 0
	v_mfma_f32_16x16x32_bf16 v[106:109], v[160:163], v[196:199], v[106:109]
	v_mfma_f32_16x16x32_bf16 v[74:77], v[168:171], v[196:199], v[74:77]
	v_mfma_f32_16x16x32_bf16 v[98:101], v[160:163], v[204:207], v[98:101]
	v_mfma_f32_16x16x32_bf16 v[62:65], v[168:171], v[204:207], v[62:65]
	v_mfma_f32_16x16x32_bf16 v[86:89], v[160:163], v[212:215], v[86:89]
	v_mfma_f32_16x16x32_bf16 v[58:61], v[168:171], v[212:215], v[58:61]
	v_mfma_f32_16x16x32_bf16 v[78:81], v[160:163], v[220:223], v[78:81]
	v_mfma_f32_16x16x32_bf16 v[54:57], v[168:171], v[220:223], v[54:57]
	s_setprio 0
	s_setprio 1
	v_mfma_f32_16x16x32_bf16 v[38:41], v[172:175], v[192:195], 0
	v_mfma_f32_16x16x32_bf16 v[22:25], v[184:187], v[192:195], 0
	v_mfma_f32_16x16x32_bf16 v[34:37], v[172:175], v[200:203], 0
	v_mfma_f32_16x16x32_bf16 v[14:17], v[184:187], v[200:203], 0
	v_mfma_f32_16x16x32_bf16 v[18:21], v[172:175], v[208:211], 0
	v_mfma_f32_16x16x32_bf16 v[6:9], v[184:187], v[208:211], 0
	v_mfma_f32_16x16x32_bf16 v[10:13], v[172:175], v[216:219], 0
	v_mfma_f32_16x16x32_bf16 v[2:5], v[184:187], v[216:219], 0
	v_mfma_f32_16x16x32_bf16 v[38:41], v[180:183], v[196:199], v[38:41]
	v_mfma_f32_16x16x32_bf16 v[22:25], v[188:191], v[196:199], v[22:25]
	v_mfma_f32_16x16x32_bf16 v[34:37], v[180:183], v[204:207], v[34:37]
	v_mfma_f32_16x16x32_bf16 v[14:17], v[188:191], v[204:207], v[14:17]
	v_mfma_f32_16x16x32_bf16 v[18:21], v[180:183], v[212:215], v[18:21]
	v_mfma_f32_16x16x32_bf16 v[6:9], v[188:191], v[212:215], v[6:9]
	v_mfma_f32_16x16x32_bf16 v[10:13], v[180:183], v[220:223], v[10:13]
	v_mfma_f32_16x16x32_bf16 v[2:5], v[188:191], v[220:223], v[2:5]
	s_setprio 0
	s_barrier
	s_branch .Lmy_mid_oproj

.Lmy_mid_oproj:
	s_add_i32 s33, 0, 0x18000
	s_add_i32 s51, 0, 0x1c000
	v_add_u32_e32 v168, s33, v152
	v_add_u32_e32 v188, s51, v152
	ds_read_b128 v[156:159], v168
	ds_read_b128 v[160:163], v168 offset:1024
	ds_read_b128 v[164:167], v168 offset:2048
	ds_read_b128 v[168:171], v168 offset:3072
	ds_read_b128 v[172:175], v188
	ds_read_b128 v[180:183], v188 offset:1024
	ds_read_b128 v[184:187], v188 offset:2048
	ds_read_b128 v[188:191], v188 offset:3072
	s_add_u32 s62, s84, 0x40000
	s_addc_u32 s63, s85, 0
	s_mov_b32 m0, s48
	v_lshl_add_u64 v[230:231], s[62:63], 0, v[0:1]
	ds_read_b128 v[192:195], v155 offset:32768
	ds_read_b128 v[196:199], v155 offset:33792
	ds_read_b128 v[200:203], v155 offset:34816
	ds_read_b128 v[204:207], v155 offset:35840
	ds_read_b128 v[208:211], v155 offset:36864
	ds_read_b128 v[212:215], v155 offset:37888
	ds_read_b128 v[216:219], v155 offset:38912
	ds_read_b128 v[220:223], v155 offset:39936
	global_load_lds_dwordx4 v[230:231], off
	v_lshl_add_u64 v[230:231], s[62:63], 0, v[130:131]
	s_mov_b32 m0, s49
	s_nop 0
	global_load_lds_dwordx4 v[230:231], off
	s_waitcnt vmcnt(8)
	s_waitcnt lgkmcnt(0)
	s_barrier
	s_setprio 1
	s_waitcnt lgkmcnt(0)
	v_mfma_f32_16x16x32_bf16 v[122:125], v[156:159], v[192:195], v[122:125]
	v_mfma_f32_16x16x32_bf16 v[102:105], v[164:167], v[192:195], v[102:105]
	v_mfma_f32_16x16x32_bf16 v[118:121], v[156:159], v[200:203], v[118:121]
	v_mfma_f32_16x16x32_bf16 v[94:97], v[164:167], v[200:203], v[94:97]
	v_mfma_f32_16x16x32_bf16 v[114:117], v[156:159], v[208:211], v[114:117]
	v_mfma_f32_16x16x32_bf16 v[90:93], v[164:167], v[208:211], v[90:93]
	v_mfma_f32_16x16x32_bf16 v[110:113], v[156:159], v[216:219], v[110:113]
	v_mfma_f32_16x16x32_bf16 v[82:85], v[164:167], v[216:219], v[82:85]
	v_mfma_f32_16x16x32_bf16 v[122:125], v[160:163], v[196:199], v[122:125]
	v_mfma_f32_16x16x32_bf16 v[102:105], v[168:171], v[196:199], v[102:105]
	v_mfma_f32_16x16x32_bf16 v[118:121], v[160:163], v[204:207], v[118:121]
	v_mfma_f32_16x16x32_bf16 v[94:97], v[168:171], v[204:207], v[94:97]
	v_mfma_f32_16x16x32_bf16 v[114:117], v[160:163], v[212:215], v[114:117]
	v_mfma_f32_16x16x32_bf16 v[90:93], v[168:171], v[212:215], v[90:93]
	v_mfma_f32_16x16x32_bf16 v[110:113], v[160:163], v[220:223], v[110:113]
	v_mfma_f32_16x16x32_bf16 v[82:85], v[168:171], v[220:223], v[82:85]
	s_setprio 0
	s_setprio 1
	v_mfma_f32_16x16x32_bf16 v[70:73], v[172:175], v[192:195], v[70:73]
	v_mfma_f32_16x16x32_bf16 v[126:129], v[184:187], v[192:195], v[126:129]
	v_mfma_f32_16x16x32_bf16 v[66:69], v[172:175], v[200:203], v[66:69]
	v_mfma_f32_16x16x32_bf16 v[42:45], v[184:187], v[200:203], v[42:45]
	v_mfma_f32_16x16x32_bf16 v[50:53], v[172:175], v[208:211], v[50:53]
	v_mfma_f32_16x16x32_bf16 v[30:33], v[184:187], v[208:211], v[30:33]
	v_mfma_f32_16x16x32_bf16 v[46:49], v[172:175], v[216:219], v[46:49]
	v_mfma_f32_16x16x32_bf16 v[26:29], v[184:187], v[216:219], v[26:29]
	v_mfma_f32_16x16x32_bf16 v[70:73], v[180:183], v[196:199], v[70:73]
	v_mfma_f32_16x16x32_bf16 v[126:129], v[188:191], v[196:199], v[126:129]
	v_mfma_f32_16x16x32_bf16 v[66:69], v[180:183], v[204:207], v[66:69]
	v_mfma_f32_16x16x32_bf16 v[42:45], v[188:191], v[204:207], v[42:45]
	v_mfma_f32_16x16x32_bf16 v[50:53], v[180:183], v[212:215], v[50:53]
	v_mfma_f32_16x16x32_bf16 v[30:33], v[188:191], v[212:215], v[30:33]
	v_mfma_f32_16x16x32_bf16 v[46:49], v[180:183], v[220:223], v[46:49]
	v_mfma_f32_16x16x32_bf16 v[26:29], v[188:191], v[220:223], v[26:29]
	s_setprio 0
	s_barrier
	s_add_i32 s33, s33, s79
	v_lshl_add_u64 v[176:177], v[176:177], 0, s[74:75]
	s_mov_b32 m0, s33
	ds_read_b128 v[192:195], v155 offset:49152
	ds_read_b128 v[196:199], v155 offset:50176
	ds_read_b128 v[200:203], v155 offset:51200
	ds_read_b128 v[204:207], v155 offset:52224
	ds_read_b128 v[208:211], v155 offset:53248
	ds_read_b128 v[212:215], v155 offset:54272
	ds_read_b128 v[216:219], v155 offset:55296
	ds_read_b128 v[220:223], v155 offset:56320
	global_load_lds_dwordx4 v[176:177], off
	s_add_i32 m0, s33, 0x2000
	s_add_u32 s62, s80, 0x40080
	v_lshl_add_u64 v[176:177], v[224:225], 0, s[74:75]
	s_addc_u32 s63, s81, 0
	s_add_i32 s33, s51, s79
	global_load_lds_dwordx4 v[176:177], off
	v_lshl_add_u64 v[176:177], s[62:63], 0, v[0:1]
	s_mov_b32 m0, s33
	s_nop 0
	global_load_lds_dwordx4 v[176:177], off
	v_lshl_add_u64 v[176:177], s[62:63], 0, v[130:131]
	s_add_i32 m0, s33, 0x2000
	s_nop 0
	global_load_lds_dwordx4 v[176:177], off
	v_lshl_add_u64 v[176:177], v[226:227], 0, s[74:75]
	s_mov_b32 m0, s83
	s_nop 0
	global_load_lds_dwordx4 v[176:177], off
	v_lshl_add_u64 v[176:177], v[228:229], 0, s[74:75]
	s_mov_b32 m0, s70
	s_nop 0
	global_load_lds_dwordx4 v[176:177], off
	s_waitcnt vmcnt(8)
	s_waitcnt lgkmcnt(0)
	s_barrier
	s_setprio 1
	s_waitcnt lgkmcnt(0)
	v_mfma_f32_16x16x32_bf16 v[106:109], v[156:159], v[192:195], v[106:109]
	v_mfma_f32_16x16x32_bf16 v[74:77], v[164:167], v[192:195], v[74:77]
	v_mfma_f32_16x16x32_bf16 v[98:101], v[156:159], v[200:203], v[98:101]
	v_mfma_f32_16x16x32_bf16 v[62:65], v[164:167], v[200:203], v[62:65]
	v_mfma_f32_16x16x32_bf16 v[86:89], v[156:159], v[208:211], v[86:89]
	v_mfma_f32_16x16x32_bf16 v[58:61], v[164:167], v[208:211], v[58:61]
	v_mfma_f32_16x16x32_bf16 v[78:81], v[156:159], v[216:219], v[78:81]
	v_mfma_f32_16x16x32_bf16 v[54:57], v[164:167], v[216:219], v[54:57]
	v_mfma_f32_16x16x32_bf16 v[106:109], v[160:163], v[196:199], v[106:109]
	v_mfma_f32_16x16x32_bf16 v[74:77], v[168:171], v[196:199], v[74:77]
	v_mfma_f32_16x16x32_bf16 v[98:101], v[160:163], v[204:207], v[98:101]
	v_mfma_f32_16x16x32_bf16 v[62:65], v[168:171], v[204:207], v[62:65]
	v_mfma_f32_16x16x32_bf16 v[86:89], v[160:163], v[212:215], v[86:89]
	v_mfma_f32_16x16x32_bf16 v[58:61], v[168:171], v[212:215], v[58:61]
	v_mfma_f32_16x16x32_bf16 v[78:81], v[160:163], v[220:223], v[78:81]
	v_mfma_f32_16x16x32_bf16 v[54:57], v[168:171], v[220:223], v[54:57]
	s_setprio 0
	s_setprio 1
	v_mfma_f32_16x16x32_bf16 v[38:41], v[172:175], v[192:195], v[38:41]
	v_mfma_f32_16x16x32_bf16 v[22:25], v[184:187], v[192:195], v[22:25]
	v_mfma_f32_16x16x32_bf16 v[34:37], v[172:175], v[200:203], v[34:37]
	v_mfma_f32_16x16x32_bf16 v[14:17], v[184:187], v[200:203], v[14:17]
	v_mfma_f32_16x16x32_bf16 v[18:21], v[172:175], v[208:211], v[18:21]
	v_mfma_f32_16x16x32_bf16 v[6:9], v[184:187], v[208:211], v[6:9]
	v_mfma_f32_16x16x32_bf16 v[10:13], v[172:175], v[216:219], v[10:13]
	v_mfma_f32_16x16x32_bf16 v[2:5], v[184:187], v[216:219], v[2:5]
	v_mfma_f32_16x16x32_bf16 v[38:41], v[180:183], v[196:199], v[38:41]
	v_mfma_f32_16x16x32_bf16 v[22:25], v[188:191], v[196:199], v[22:25]
	v_mfma_f32_16x16x32_bf16 v[34:37], v[180:183], v[204:207], v[34:37]
	v_mfma_f32_16x16x32_bf16 v[14:17], v[188:191], v[204:207], v[14:17]
	v_mfma_f32_16x16x32_bf16 v[18:21], v[180:183], v[212:215], v[18:21]
	v_mfma_f32_16x16x32_bf16 v[6:9], v[188:191], v[212:215], v[6:9]
	v_mfma_f32_16x16x32_bf16 v[10:13], v[180:183], v[220:223], v[10:13]
	v_mfma_f32_16x16x32_bf16 v[2:5], v[188:191], v[220:223], v[2:5]
	s_setprio 0
	s_barrier
	s_add_u32 s59, s59, 0x100
	s_addc_u32 s76, s76, 0
	s_cmp_ge_u32 s82, s29
	s_mov_b64 s[62:63], s[64:65]
	s_mov_b32 s80, s82
	s_cbranch_scc0 .LBB0_1164
	s_and_b64 vcc, exec, s[22:23]
	s_cbranch_vccz .LBB0_1167
	s_barrier

.LBB0_1170:
	s_nop 0
	s_mov_b32 s86, s42
	s_mov_b32 s16, s30
	s_mov_b32 s14, s28
	s_andn2_b64 vcc, exec, s[34:35]
	s_cbranch_vccnz .LBB0_1172
	s_branch .LBB0_1173
